# last-layer residual epilogue tail group and norm2 first column group: serial loads batched
# speedup vs baseline: 1.0016x; 1.0016x over previous
.LBB0_908:
	s_or_b64 exec, exec, s[0:1]
	v_lshl_add_u64 v[22:23], v[18:19], 0, v[154:155]
	global_load_dwordx4 v[18:21], v[22:23], off
	global_load_dwordx4 v[176:179], v[22:23], off offset:64
	global_load_dwordx4 v[180:183], v[22:23], off offset:512
	global_load_dwordx4 v[184:187], v[22:23], off offset:576
	v_readlane_b32 s0, v255, 10
	v_readlane_b32 s1, v255, 11
	s_and_b64 vcc, exec, s[42:43]
	s_mov_b32 s62, s18
	v_lshl_add_u64 v[16:17], s[0:1], 0, v[16:17]
	v_lshl_add_u64 v[16:17], v[16:17], 0, v[154:155]
	s_mov_b32 s61, s44
	s_mov_b64 s[50:51], s[48:49]
	s_mov_b64 s[52:53], s[46:47]
	s_waitcnt vmcnt(0) lgkmcnt(0)
	v_pk_fma_f32 v[12:13], v[12:13], v[142:143], v[18:19]
	v_pk_fma_f32 v[14:15], v[14:15], v[144:145], v[20:21]
	global_store_dwordx4 v[16:17], v[12:15], off
	v_pk_fma_f32 v[8:9], v[8:9], v[138:139], v[176:177]
	v_pk_fma_f32 v[10:11], v[10:11], v[140:141], v[178:179]
	global_store_dwordx4 v[16:17], v[8:11], off offset:64
	v_pk_fma_f32 v[4:5], v[4:5], v[134:135], v[180:181]
	v_pk_fma_f32 v[6:7], v[6:7], v[136:137], v[182:183]
	global_store_dwordx4 v[16:17], v[4:7], off offset:512
	v_pk_fma_f32 v[0:1], v[0:1], v[130:131], v[184:185]
	v_pk_fma_f32 v[2:3], v[2:3], v[132:133], v[186:187]
	global_store_dwordx4 v[16:17], v[0:3], off offset:576
	s_cbranch_vccnz .LBB0_951

.LBB0_2181:
	v_readlane_b32 s6, v255, 16
	v_readlane_b32 s4, v255, 10
	v_readlane_b32 s7, v255, 17
	v_readlane_b32 s5, v255, 11
	v_add_u32_e32 v128, 0xffffc000, v16
	v_ashrrev_i32_e32 v17, 31, v16
	v_cmp_gt_i32_e32 vcc, s33, v16
	v_mov_b32_e32 v2, s7
	v_mov_b32_e32 v3, s5
	v_cndmask_b32_e32 v1, 0, v17, vcc
	v_cndmask_b32_e32 v0, v128, v16, vcc
	v_cndmask_b32_e32 v3, v2, v3, vcc
	v_mov_b32_e32 v2, s6
	v_mov_b32_e32 v4, s4
	v_cndmask_b32_e32 v2, v2, v4, vcc
	v_lshlrev_b64 v[0:1], 12, v[0:1]
	v_lshl_add_u64 v[0:1], v[2:3], 0, v[0:1]
	v_mov_b32_e32 v35, v129
	v_lshl_add_u64 v[0:1], v[0:1], 0, v[34:35]
	global_load_dwordx4 v[12:15], v[0:1], off
	global_load_dwordx4 v[8:11], v[0:1], off offset:1024
	global_load_dwordx4 v[4:7], v[0:1], off offset:2048
	s_nop 0
	global_load_dwordx4 v[0:3], v[0:1], off offset:3072
	s_movk_i32 s4, 0x3fff
	v_cmp_lt_i32_e32 vcc, s4, v16
	s_and_b64 s[4:5], s[0:1], vcc
	s_and_saveexec_b64 s[42:43], s[4:5]
	s_cbranch_execz .LBB0_2180
	v_lshlrev_b64 v[42:43], 12, v[128:129]
	v_lshl_add_u64 v[50:51], v[28:29], 0, v[42:43]
	v_lshlrev_b64 v[62:63], 12, v[16:17]
	v_add_co_u32_e32 v48, vcc, 0x200000, v50
	s_nop 1
	v_addc_co_u32_e32 v49, vcc, 0, v51, vcc
	v_add_co_u32_e32 v46, vcc, 0x400000, v50
	s_nop 1
	v_addc_co_u32_e32 v47, vcc, 0, v51, vcc
	v_add_co_u32_e32 v44, vcc, 0x600000, v50
	s_nop 1
	v_addc_co_u32_e32 v45, vcc, 0, v51, vcc
	global_load_dwordx4 v[84:87], v[50:51], off
	global_load_dwordx4 v[88:91], v[48:49], off
	global_load_dwordx4 v[92:95], v[46:47], off
	global_load_dwordx4 v[96:99], v[44:45], off
	global_load_dwordx4 v[100:103], v[20:21], off
	s_waitcnt vmcnt(0)
	v_pk_add_f32 v[64:65], v[86:87], 0 op_sel_hi:[1,0]
	v_pk_add_f32 v[42:43], v[84:85], 0 op_sel_hi:[1,0]
	v_pk_add_f32 v[64:65], v[64:65], v[90:91]
	v_pk_add_f32 v[42:43], v[42:43], v[88:89]
	v_pk_add_f32 v[64:65], v[64:65], v[94:95]
	v_pk_add_f32 v[42:43], v[42:43], v[92:93]
	v_pk_add_f32 v[64:65], v[64:65], v[98:99]
	v_pk_add_f32 v[42:43], v[42:43], v[96:97]
	v_pk_fma_f32 v[14:15], v[64:65], v[102:103], v[14:15]
	v_pk_fma_f32 v[12:13], v[42:43], v[100:101], v[12:13]
	global_load_dwordx4 v[84:87], v[50:51], off offset:1024
	global_load_dwordx4 v[88:91], v[48:49], off offset:1024
	global_load_dwordx4 v[92:95], v[46:47], off offset:1024
	global_load_dwordx4 v[96:99], v[44:45], off offset:1024
	global_load_dwordx4 v[100:103], v[22:23], off
	s_waitcnt vmcnt(0)
	v_lshl_add_u64 v[42:43], v[30:31], 0, v[62:63]
	global_store_dwordx4 v[42:43], v[12:15], off
	v_pk_add_f32 v[62:63], v[86:87], 0 op_sel_hi:[1,0]
	v_pk_add_f32 v[64:65], v[84:85], 0 op_sel_hi:[1,0]
	v_pk_add_f32 v[62:63], v[62:63], v[90:91]
	v_pk_add_f32 v[64:65], v[64:65], v[88:89]
	v_pk_add_f32 v[62:63], v[62:63], v[94:95]
	v_pk_add_f32 v[64:65], v[64:65], v[92:93]
	v_pk_add_f32 v[62:63], v[62:63], v[98:99]
	v_pk_add_f32 v[64:65], v[64:65], v[96:97]
	v_pk_fma_f32 v[10:11], v[62:63], v[102:103], v[10:11]
	v_pk_fma_f32 v[8:9], v[64:65], v[100:101], v[8:9]
	global_load_dwordx4 v[84:87], v[50:51], off offset:2048
	global_load_dwordx4 v[88:91], v[48:49], off offset:2048
	global_load_dwordx4 v[92:95], v[46:47], off offset:2048
	global_load_dwordx4 v[96:99], v[44:45], off offset:2048
	global_load_dwordx4 v[100:103], v[24:25], off
	s_waitcnt vmcnt(0)
	v_pk_add_f32 v[62:63], v[86:87], 0 op_sel_hi:[1,0]
	v_pk_add_f32 v[64:65], v[84:85], 0 op_sel_hi:[1,0]
	v_pk_add_f32 v[62:63], v[62:63], v[90:91]
	v_pk_add_f32 v[64:65], v[64:65], v[88:89]
	v_pk_add_f32 v[62:63], v[62:63], v[94:95]
	v_pk_add_f32 v[64:65], v[64:65], v[92:93]
	v_pk_add_f32 v[62:63], v[62:63], v[98:99]
	v_pk_add_f32 v[64:65], v[64:65], v[96:97]
	v_pk_fma_f32 v[6:7], v[62:63], v[102:103], v[6:7]
	v_pk_fma_f32 v[4:5], v[64:65], v[100:101], v[4:5]
	global_load_dwordx4 v[84:87], v[50:51], off offset:3072
	global_load_dwordx4 v[88:91], v[48:49], off offset:3072
	global_load_dwordx4 v[92:95], v[46:47], off offset:3072
	global_load_dwordx4 v[96:99], v[44:45], off offset:3072
	global_load_dwordx4 v[100:103], v[26:27], off
	s_waitcnt vmcnt(0)
	v_pk_add_f32 v[58:59], v[84:85], 0 op_sel_hi:[1,0]
	v_pk_add_f32 v[60:61], v[86:87], 0 op_sel_hi:[1,0]
	global_store_dwordx4 v[42:43], v[8:11], off offset:1024
	global_store_dwordx4 v[42:43], v[4:7], off offset:2048
	v_pk_add_f32 v[58:59], v[58:59], v[88:89]
	v_pk_add_f32 v[50:51], v[60:61], v[90:91]
	v_pk_add_f32 v[48:49], v[50:51], v[94:95]
	v_pk_add_f32 v[50:51], v[58:59], v[92:93]
	v_pk_add_f32 v[48:49], v[48:49], v[98:99]
	v_pk_add_f32 v[50:51], v[50:51], v[96:97]
	v_pk_fma_f32 v[2:3], v[48:49], v[102:103], v[2:3]
	v_pk_fma_f32 v[0:1], v[50:51], v[100:101], v[0:1]
	global_store_dwordx4 v[42:43], v[0:3], off offset:3072
	s_branch .LBB0_2180

.LBB0_2546:
	s_or_b64 exec, exec, s[8:9]
	v_lshl_add_u64 v[22:23], v[18:19], 0, v[154:155]
	global_load_dwordx4 v[18:21], v[22:23], off
	global_load_dwordx4 v[176:179], v[22:23], off offset:64
	global_load_dwordx4 v[180:183], v[22:23], off offset:512
	global_load_dwordx4 v[184:187], v[22:23], off offset:576
	v_readlane_b32 s8, v255, 10
	v_readlane_b32 s9, v255, 11
	s_and_b64 vcc, exec, s[42:43]
	s_mov_b32 s61, s58
	v_lshl_add_u64 v[16:17], s[8:9], 0, v[16:17]
	v_lshl_add_u64 v[16:17], v[16:17], 0, v[154:155]
	s_mov_b32 s60, s59
	s_mov_b64 s[48:49], s[18:19]
	s_mov_b64 s[46:47], s[0:1]
	s_waitcnt vmcnt(0) lgkmcnt(0)
	v_pk_fma_f32 v[12:13], v[12:13], v[142:143], v[18:19]
	v_pk_fma_f32 v[14:15], v[14:15], v[144:145], v[20:21]
	global_store_dwordx4 v[16:17], v[12:15], off
	v_pk_fma_f32 v[8:9], v[8:9], v[138:139], v[176:177]
	v_pk_fma_f32 v[10:11], v[10:11], v[140:141], v[178:179]
	global_store_dwordx4 v[16:17], v[8:11], off offset:64
	v_pk_fma_f32 v[4:5], v[4:5], v[134:135], v[180:181]
	v_pk_fma_f32 v[6:7], v[6:7], v[136:137], v[182:183]
	global_store_dwordx4 v[16:17], v[4:7], off offset:512
	v_pk_fma_f32 v[0:1], v[0:1], v[130:131], v[184:185]
	v_pk_fma_f32 v[2:3], v[2:3], v[132:133], v[186:187]
	global_store_dwordx4 v[16:17], v[0:3], off offset:576
	s_cbranch_vccnz .LBB0_2593
